# main GEMM K-loop: vmcnt and lgkmcnt waits merged, the redundant post-barrier lgkmcnt(0) removed
# speedup vs baseline: 1.0020x; 1.0020x over previous
.LBB0_744:
	s_add_i32 s35, s10, 2
	s_add_u32 s37, s8, 0x80
	s_addc_u32 s11, s9, 0
	s_add_i32 s72, 0, 0x10000
	s_cmp_eq_u32 s65, s10
	s_cselect_b32 s11, s29, s11
	s_cselect_b32 s10, s28, s37
	v_add_u32_e32 v160, s72, v183
	s_cselect_b32 s81, s31, s34
	s_cselect_b32 s80, s30, s27
	s_add_i32 s37, 0, 0x14000
	ds_read_b128 v[130:133], v160
	ds_read_b128 v[134:137], v160 offset:1024
	ds_read_b128 v[156:159], v160 offset:2048
	ds_read_b128 v[186:189], v160 offset:3072
	v_add_u32_e32 v160, s37, v183
	ds_read_b128 v[190:193], v160
	ds_read_b128 v[194:197], v160 offset:1024
	ds_read_b128 v[198:201], v160 offset:2048
	ds_read_b128 v[202:205], v160 offset:3072
	v_lshl_add_u64 v[160:161], s[8:9], 0, v[150:151]
	s_add_i32 m0, s45, 0xc000
	ds_read_b128 v[206:209], v185
	ds_read_b128 v[210:213], v185 offset:1024
	ds_read_b128 v[214:217], v185 offset:2048
	ds_read_b128 v[218:221], v185 offset:3072
	ds_read_b128 v[222:225], v185 offset:4096
	ds_read_b128 v[226:229], v185 offset:5120
	ds_read_b128 v[230:233], v185 offset:6144
	ds_read_b128 v[234:237], v185 offset:7168
	global_load_lds_dwordx4 v[160:161], off
	v_lshl_add_u64 v[160:161], s[8:9], 0, v[152:153]
	s_add_i32 m0, s45, 0xe000
	s_nop 0
	global_load_lds_dwordx4 v[160:161], off
	s_waitcnt vmcnt(8) lgkmcnt(0)
	s_barrier
	s_setprio 1
	v_mfma_f32_16x16x32_bf16 v[126:129], v[130:133], v[206:209], v[126:129]
	v_mfma_f32_16x16x32_bf16 v[122:125], v[156:159], v[206:209], v[122:125]
	v_mfma_f32_16x16x32_bf16 v[110:113], v[130:133], v[214:217], v[110:113]
	v_mfma_f32_16x16x32_bf16 v[106:109], v[156:159], v[214:217], v[106:109]
	v_mfma_f32_16x16x32_bf16 v[94:97], v[130:133], v[222:225], v[94:97]
	v_mfma_f32_16x16x32_bf16 v[90:93], v[156:159], v[222:225], v[90:93]
	v_mfma_f32_16x16x32_bf16 v[78:81], v[130:133], v[230:233], v[78:81]
	v_mfma_f32_16x16x32_bf16 v[74:77], v[156:159], v[230:233], v[74:77]
	v_mfma_f32_16x16x32_bf16 v[126:129], v[134:137], v[210:213], v[126:129]
	v_mfma_f32_16x16x32_bf16 v[122:125], v[186:189], v[210:213], v[122:125]
	v_mfma_f32_16x16x32_bf16 v[110:113], v[134:137], v[218:221], v[110:113]
	v_mfma_f32_16x16x32_bf16 v[106:109], v[186:189], v[218:221], v[106:109]
	v_mfma_f32_16x16x32_bf16 v[94:97], v[134:137], v[226:229], v[94:97]
	v_mfma_f32_16x16x32_bf16 v[90:93], v[186:189], v[226:229], v[90:93]
	v_mfma_f32_16x16x32_bf16 v[78:81], v[134:137], v[234:237], v[78:81]
	v_mfma_f32_16x16x32_bf16 v[74:77], v[186:189], v[234:237], v[74:77]
	s_setprio 0
	s_setprio 1
	v_mfma_f32_16x16x32_bf16 v[118:121], v[190:193], v[206:209], v[118:121]
	v_mfma_f32_16x16x32_bf16 v[114:117], v[198:201], v[206:209], v[114:117]
	v_mfma_f32_16x16x32_bf16 v[102:105], v[190:193], v[214:217], v[102:105]
	v_mfma_f32_16x16x32_bf16 v[98:101], v[198:201], v[214:217], v[98:101]
	v_mfma_f32_16x16x32_bf16 v[86:89], v[190:193], v[222:225], v[86:89]
	v_mfma_f32_16x16x32_bf16 v[82:85], v[198:201], v[222:225], v[82:85]
	v_mfma_f32_16x16x32_bf16 v[70:73], v[190:193], v[230:233], v[70:73]
	v_mfma_f32_16x16x32_bf16 v[66:69], v[198:201], v[230:233], v[66:69]
	v_mfma_f32_16x16x32_bf16 v[118:121], v[194:197], v[210:213], v[118:121]
	v_mfma_f32_16x16x32_bf16 v[114:117], v[202:205], v[210:213], v[114:117]
	v_mfma_f32_16x16x32_bf16 v[102:105], v[194:197], v[218:221], v[102:105]
	v_mfma_f32_16x16x32_bf16 v[98:101], v[202:205], v[218:221], v[98:101]
	v_mfma_f32_16x16x32_bf16 v[86:89], v[194:197], v[226:229], v[86:89]
	v_mfma_f32_16x16x32_bf16 v[82:85], v[202:205], v[226:229], v[82:85]
	v_mfma_f32_16x16x32_bf16 v[70:73], v[194:197], v[234:237], v[70:73]
	v_mfma_f32_16x16x32_bf16 v[66:69], v[202:205], v[234:237], v[66:69]
	s_setprio 0
	s_barrier
	s_add_i32 s72, s72, s33
	v_lshl_add_u64 v[160:161], s[80:81], 0, v[0:1]
	s_mov_b32 m0, s72
	ds_read_b128 v[206:209], v185 offset:16384
	ds_read_b128 v[210:213], v185 offset:17408
	ds_read_b128 v[214:217], v185 offset:18432
	ds_read_b128 v[218:221], v185 offset:19456
	ds_read_b128 v[222:225], v185 offset:20480
	ds_read_b128 v[226:229], v185 offset:21504
	ds_read_b128 v[230:233], v185 offset:22528
	ds_read_b128 v[234:237], v185 offset:23552
	global_load_lds_dwordx4 v[160:161], off
	s_add_i32 m0, s72, 0x2000
	v_lshl_add_u64 v[238:239], s[80:81], 0, v[144:145]
	s_add_u32 s80, s80, s39
	s_addc_u32 s81, s81, 0
	s_add_i32 s37, s37, s33
	global_load_lds_dwordx4 v[238:239], off
	v_lshl_add_u64 v[240:241], s[80:81], 0, v[0:1]
	s_mov_b32 m0, s37
	v_lshl_add_u64 v[242:243], s[80:81], 0, v[144:145]
	global_load_lds_dwordx4 v[240:241], off
	s_add_i32 m0, s37, 0x2000
	v_lshl_add_u64 v[244:245], s[10:11], 0, v[146:147]
	global_load_lds_dwordx4 v[242:243], off
	s_mov_b32 m0, s45
	v_lshl_add_u64 v[246:247], s[10:11], 0, v[142:143]
	global_load_lds_dwordx4 v[244:245], off
	s_mov_b32 m0, s59
	s_nop 0
	global_load_lds_dwordx4 v[246:247], off
	s_waitcnt vmcnt(8) lgkmcnt(0)
	s_barrier
	s_setprio 1
	v_mfma_f32_16x16x32_bf16 v[62:65], v[130:133], v[206:209], v[62:65]
	v_mfma_f32_16x16x32_bf16 v[58:61], v[156:159], v[206:209], v[58:61]
	v_mfma_f32_16x16x32_bf16 v[46:49], v[130:133], v[214:217], v[46:49]
	v_mfma_f32_16x16x32_bf16 v[42:45], v[156:159], v[214:217], v[42:45]
	v_mfma_f32_16x16x32_bf16 v[30:33], v[130:133], v[222:225], v[30:33]
	v_mfma_f32_16x16x32_bf16 v[26:29], v[156:159], v[222:225], v[26:29]
	v_mfma_f32_16x16x32_bf16 v[14:17], v[130:133], v[230:233], v[14:17]
	v_mfma_f32_16x16x32_bf16 v[10:13], v[156:159], v[230:233], v[10:13]
	v_mfma_f32_16x16x32_bf16 v[62:65], v[134:137], v[210:213], v[62:65]
	v_mfma_f32_16x16x32_bf16 v[58:61], v[186:189], v[210:213], v[58:61]
	v_mfma_f32_16x16x32_bf16 v[46:49], v[134:137], v[218:221], v[46:49]
	v_mfma_f32_16x16x32_bf16 v[42:45], v[186:189], v[218:221], v[42:45]
	v_mfma_f32_16x16x32_bf16 v[30:33], v[134:137], v[226:229], v[30:33]
	v_mfma_f32_16x16x32_bf16 v[26:29], v[186:189], v[226:229], v[26:29]
	v_mfma_f32_16x16x32_bf16 v[14:17], v[134:137], v[234:237], v[14:17]
	v_mfma_f32_16x16x32_bf16 v[10:13], v[186:189], v[234:237], v[10:13]
	s_setprio 0
	s_setprio 1
	v_mfma_f32_16x16x32_bf16 v[54:57], v[190:193], v[206:209], v[54:57]
	v_mfma_f32_16x16x32_bf16 v[50:53], v[198:201], v[206:209], v[50:53]
	v_mfma_f32_16x16x32_bf16 v[38:41], v[190:193], v[214:217], v[38:41]
	v_mfma_f32_16x16x32_bf16 v[34:37], v[198:201], v[214:217], v[34:37]
	v_mfma_f32_16x16x32_bf16 v[22:25], v[190:193], v[222:225], v[22:25]
	v_mfma_f32_16x16x32_bf16 v[18:21], v[198:201], v[222:225], v[18:21]
	v_mfma_f32_16x16x32_bf16 v[6:9], v[190:193], v[230:233], v[6:9]
	v_mfma_f32_16x16x32_bf16 v[2:5], v[198:201], v[230:233], v[2:5]
	v_mfma_f32_16x16x32_bf16 v[54:57], v[194:197], v[210:213], v[54:57]
	v_mfma_f32_16x16x32_bf16 v[50:53], v[202:205], v[210:213], v[50:53]
	v_mfma_f32_16x16x32_bf16 v[38:41], v[194:197], v[218:221], v[38:41]
	v_mfma_f32_16x16x32_bf16 v[34:37], v[202:205], v[218:221], v[34:37]
	v_mfma_f32_16x16x32_bf16 v[22:25], v[194:197], v[226:229], v[22:25]
	v_mfma_f32_16x16x32_bf16 v[18:21], v[202:205], v[226:229], v[18:21]
	v_mfma_f32_16x16x32_bf16 v[6:9], v[194:197], v[234:237], v[6:9]
	v_mfma_f32_16x16x32_bf16 v[2:5], v[202:205], v[234:237], v[2:5]
	s_setprio 0
	s_barrier
	s_add_i32 s37, 0, 0x1c000
	v_add_u32_e32 v186, s66, v183
	v_add_u32_e32 v202, s37, v183
	ds_read_b128 v[130:133], v186
	ds_read_b128 v[134:137], v186 offset:1024
	ds_read_b128 v[156:159], v186 offset:2048
	ds_read_b128 v[186:189], v186 offset:3072
	ds_read_b128 v[190:193], v202
	ds_read_b128 v[194:197], v202 offset:1024
	ds_read_b128 v[198:201], v202 offset:2048
	ds_read_b128 v[202:205], v202 offset:3072
	s_add_u32 s10, s10, s0
	s_addc_u32 s11, s11, 0
	s_mov_b32 m0, s60
	v_lshl_add_u64 v[248:249], s[10:11], 0, v[146:147]
	ds_read_b128 v[206:209], v185 offset:32768
	ds_read_b128 v[210:213], v185 offset:33792
	ds_read_b128 v[214:217], v185 offset:34816
	ds_read_b128 v[218:221], v185 offset:35840
	ds_read_b128 v[222:225], v185 offset:36864
	ds_read_b128 v[226:229], v185 offset:37888
	ds_read_b128 v[230:233], v185 offset:38912
	ds_read_b128 v[234:237], v185 offset:39936
	global_load_lds_dwordx4 v[248:249], off
	v_lshl_add_u64 v[248:249], s[10:11], 0, v[142:143]
	s_mov_b32 m0, s61
	s_nop 0
	global_load_lds_dwordx4 v[248:249], off
	s_waitcnt vmcnt(8) lgkmcnt(0)
	s_barrier
	s_setprio 1
	v_mfma_f32_16x16x32_bf16 v[126:129], v[130:133], v[206:209], v[126:129]
	v_mfma_f32_16x16x32_bf16 v[122:125], v[156:159], v[206:209], v[122:125]
	v_mfma_f32_16x16x32_bf16 v[110:113], v[130:133], v[214:217], v[110:113]
	v_mfma_f32_16x16x32_bf16 v[106:109], v[156:159], v[214:217], v[106:109]
	v_mfma_f32_16x16x32_bf16 v[94:97], v[130:133], v[222:225], v[94:97]
	v_mfma_f32_16x16x32_bf16 v[90:93], v[156:159], v[222:225], v[90:93]
	v_mfma_f32_16x16x32_bf16 v[78:81], v[130:133], v[230:233], v[78:81]
	v_mfma_f32_16x16x32_bf16 v[74:77], v[156:159], v[230:233], v[74:77]
	v_mfma_f32_16x16x32_bf16 v[126:129], v[134:137], v[210:213], v[126:129]
	v_mfma_f32_16x16x32_bf16 v[122:125], v[186:189], v[210:213], v[122:125]
	v_mfma_f32_16x16x32_bf16 v[110:113], v[134:137], v[218:221], v[110:113]
	v_mfma_f32_16x16x32_bf16 v[106:109], v[186:189], v[218:221], v[106:109]
	v_mfma_f32_16x16x32_bf16 v[94:97], v[134:137], v[226:229], v[94:97]
	v_mfma_f32_16x16x32_bf16 v[90:93], v[186:189], v[226:229], v[90:93]
	v_mfma_f32_16x16x32_bf16 v[78:81], v[134:137], v[234:237], v[78:81]
	v_mfma_f32_16x16x32_bf16 v[74:77], v[186:189], v[234:237], v[74:77]
	s_setprio 0
	s_setprio 1
	v_mfma_f32_16x16x32_bf16 v[118:121], v[190:193], v[206:209], v[118:121]
	v_mfma_f32_16x16x32_bf16 v[114:117], v[198:201], v[206:209], v[114:117]
	v_mfma_f32_16x16x32_bf16 v[102:105], v[190:193], v[214:217], v[102:105]
	v_mfma_f32_16x16x32_bf16 v[98:101], v[198:201], v[214:217], v[98:101]
	v_mfma_f32_16x16x32_bf16 v[86:89], v[190:193], v[222:225], v[86:89]
	v_mfma_f32_16x16x32_bf16 v[82:85], v[198:201], v[222:225], v[82:85]
	v_mfma_f32_16x16x32_bf16 v[70:73], v[190:193], v[230:233], v[70:73]
	v_mfma_f32_16x16x32_bf16 v[66:69], v[198:201], v[230:233], v[66:69]
	v_mfma_f32_16x16x32_bf16 v[118:121], v[194:197], v[210:213], v[118:121]
	v_mfma_f32_16x16x32_bf16 v[114:117], v[202:205], v[210:213], v[114:117]
	v_mfma_f32_16x16x32_bf16 v[102:105], v[194:197], v[218:221], v[102:105]
	v_mfma_f32_16x16x32_bf16 v[98:101], v[202:205], v[218:221], v[98:101]
	v_mfma_f32_16x16x32_bf16 v[86:89], v[194:197], v[226:229], v[86:89]
	v_mfma_f32_16x16x32_bf16 v[82:85], v[202:205], v[226:229], v[82:85]
	v_mfma_f32_16x16x32_bf16 v[70:73], v[194:197], v[234:237], v[70:73]
	v_mfma_f32_16x16x32_bf16 v[66:69], v[202:205], v[234:237], v[66:69]
	s_setprio 0
	s_barrier
	s_add_i32 s10, s66, s33
	v_lshl_add_u64 v[160:161], v[160:161], 0, s[54:55]
	s_mov_b32 m0, s10
	ds_read_b128 v[206:209], v185 offset:49152
	ds_read_b128 v[210:213], v185 offset:50176
	ds_read_b128 v[214:217], v185 offset:51200
	ds_read_b128 v[218:221], v185 offset:52224
	ds_read_b128 v[222:225], v185 offset:53248
	ds_read_b128 v[226:229], v185 offset:54272
	ds_read_b128 v[230:233], v185 offset:55296
	ds_read_b128 v[234:237], v185 offset:56320
	global_load_lds_dwordx4 v[160:161], off
	v_lshl_add_u64 v[160:161], v[238:239], 0, s[54:55]
	s_add_i32 m0, s10, 0x2000
	s_add_i32 s10, s37, s33
	global_load_lds_dwordx4 v[160:161], off
	v_lshl_add_u64 v[160:161], v[240:241], 0, s[54:55]
	s_mov_b32 m0, s10
	s_nop 0
	global_load_lds_dwordx4 v[160:161], off
	v_lshl_add_u64 v[160:161], v[242:243], 0, s[54:55]
	s_add_i32 m0, s10, 0x2000
	s_nop 0
	global_load_lds_dwordx4 v[160:161], off
	v_lshl_add_u64 v[160:161], v[244:245], 0, s[54:55]
	s_mov_b32 m0, s63
	s_nop 0
	global_load_lds_dwordx4 v[160:161], off
	v_lshl_add_u64 v[160:161], v[246:247], 0, s[54:55]
	s_mov_b32 m0, s64
	s_nop 0
	global_load_lds_dwordx4 v[160:161], off
	s_waitcnt vmcnt(8) lgkmcnt(0)
	s_barrier
	s_setprio 1
	v_mfma_f32_16x16x32_bf16 v[62:65], v[130:133], v[206:209], v[62:65]
	v_mfma_f32_16x16x32_bf16 v[58:61], v[156:159], v[206:209], v[58:61]
	v_mfma_f32_16x16x32_bf16 v[46:49], v[130:133], v[214:217], v[46:49]
	v_mfma_f32_16x16x32_bf16 v[42:45], v[156:159], v[214:217], v[42:45]
	v_mfma_f32_16x16x32_bf16 v[30:33], v[130:133], v[222:225], v[30:33]
	v_mfma_f32_16x16x32_bf16 v[26:29], v[156:159], v[222:225], v[26:29]
	v_mfma_f32_16x16x32_bf16 v[14:17], v[130:133], v[230:233], v[14:17]
	v_mfma_f32_16x16x32_bf16 v[10:13], v[156:159], v[230:233], v[10:13]
	v_mfma_f32_16x16x32_bf16 v[62:65], v[134:137], v[210:213], v[62:65]
	v_mfma_f32_16x16x32_bf16 v[58:61], v[186:189], v[210:213], v[58:61]
	v_mfma_f32_16x16x32_bf16 v[46:49], v[134:137], v[218:221], v[46:49]
	v_mfma_f32_16x16x32_bf16 v[42:45], v[186:189], v[218:221], v[42:45]
	v_mfma_f32_16x16x32_bf16 v[30:33], v[134:137], v[226:229], v[30:33]
	v_mfma_f32_16x16x32_bf16 v[26:29], v[186:189], v[226:229], v[26:29]
	v_mfma_f32_16x16x32_bf16 v[14:17], v[134:137], v[234:237], v[14:17]
	v_mfma_f32_16x16x32_bf16 v[10:13], v[186:189], v[234:237], v[10:13]
	s_setprio 0
	s_setprio 1
	v_mfma_f32_16x16x32_bf16 v[54:57], v[190:193], v[206:209], v[54:57]
	v_mfma_f32_16x16x32_bf16 v[50:53], v[198:201], v[206:209], v[50:53]
	v_mfma_f32_16x16x32_bf16 v[38:41], v[190:193], v[214:217], v[38:41]
	v_mfma_f32_16x16x32_bf16 v[34:37], v[198:201], v[214:217], v[34:37]
	v_mfma_f32_16x16x32_bf16 v[22:25], v[190:193], v[222:225], v[22:25]
	v_mfma_f32_16x16x32_bf16 v[18:21], v[198:201], v[222:225], v[18:21]
	v_mfma_f32_16x16x32_bf16 v[6:9], v[190:193], v[230:233], v[6:9]
	v_mfma_f32_16x16x32_bf16 v[2:5], v[198:201], v[230:233], v[2:5]
	v_mfma_f32_16x16x32_bf16 v[54:57], v[194:197], v[210:213], v[54:57]
	v_mfma_f32_16x16x32_bf16 v[50:53], v[202:205], v[210:213], v[50:53]
	v_mfma_f32_16x16x32_bf16 v[38:41], v[194:197], v[218:221], v[38:41]
	v_mfma_f32_16x16x32_bf16 v[34:37], v[202:205], v[218:221], v[34:37]
	v_mfma_f32_16x16x32_bf16 v[22:25], v[194:197], v[226:229], v[22:25]
	v_mfma_f32_16x16x32_bf16 v[18:21], v[202:205], v[226:229], v[18:21]
	v_mfma_f32_16x16x32_bf16 v[6:9], v[194:197], v[234:237], v[6:9]
	v_mfma_f32_16x16x32_bf16 v[2:5], v[202:205], v[234:237], v[2:5]
	s_setprio 0
	s_barrier
	s_add_u32 s8, s8, 0x100
	s_addc_u32 s9, s9, 0
	s_add_u32 s27, s27, 0x100
	s_addc_u32 s34, s34, 0
	s_cmp_ge_u32 s35, s62
	s_mov_b32 s10, s35
	s_cbranch_scc0 .LBB0_744
	s_and_b64 vcc, exec, s[76:77]
	s_cbranch_vccz .LBB0_747
	s_barrier
